# P3 epilogue x loads software-pipelined + nt; island barriers skip L2 writeback when island is on one XCD
# baseline (speedup 1.0000x reference)
.LBB0_509:
	s_andn2_saveexec_b64 s[4:5], s[4:5]
	s_cbranch_execz .LBB0_529
	s_mov_b64 s[4:5], exec
	v_cmp_eq_u32_e32 vcc, 1, v0
	s_cbranch_vccnz .Lnowb_1
	buffer_wbl2 sc1
.Lnowb_1:
	s_waitcnt lgkmcnt(0)
	s_waitcnt vmcnt(0)
	v_mbcnt_lo_u32_b32 v1, s4, 0
	v_mbcnt_hi_u32_b32 v1, s5, v1
	v_cmp_eq_u32_e32 vcc, 0, v1
	s_and_saveexec_b64 s[8:9], vcc
	s_cbranch_execz .LBB0_512
	s_bcnt1_i32_b64 s4, s[4:5]
	v_mov_b32_e32 v2, 0x3000
	v_mov_b32_e32 v3, s4
	global_atomic_add v2, v2, v3, s[66:67] offset:1024 sc0

.LBB0_577:
	s_andn2_saveexec_b64 s[4:5], s[4:5]
	s_cbranch_execz .LBB0_597
	s_mov_b64 s[6:7], exec
	v_cmp_eq_u32_e32 vcc, 1, v0
	s_cbranch_vccnz .Lnowb_2
	buffer_wbl2 sc1
.Lnowb_2:
	s_waitcnt lgkmcnt(0)
	s_waitcnt vmcnt(0)
	v_mbcnt_lo_u32_b32 v1, s6, 0
	v_mbcnt_hi_u32_b32 v1, s7, v1
	v_cmp_eq_u32_e32 vcc, 0, v1
	s_and_saveexec_b64 s[8:9], vcc
	s_cbranch_execz .LBB0_580
	s_bcnt1_i32_b64 s6, s[6:7]
	v_mov_b32_e32 v2, 0x3000
	v_mov_b32_e32 v3, s6
	global_atomic_add v2, v2, v3, s[66:67] offset:1024 sc0

.LBB0_620:
	s_ashr_i32 s2, s50, 3
	s_lshl_b32 s1, s50, 8
	s_mul_hi_i32 s3, s2, 0x9000
	s_mul_i32 s2, s2, 0x9000
	v_lshl_or_b32 v176, s0, 8, v185
	s_add_u32 s2, s64, s2
	s_addc_u32 s3, s65, s3
	v_ashrrev_i32_e32 v177, 31, v176
	v_lshl_add_u64 v[32:33], v[176:177], 2, s[2:3]
	s_mov_b64 s[2:3], 0x2000
	v_lshl_add_u64 v[34:35], v[32:33], 0, s[2:3]
	s_mov_b64 s[2:3], 0x4000
	v_lshl_add_u64 v[36:37], v[32:33], 0, s[2:3]
	s_movk_i32 s2, 0x2000
	v_add_co_u32_e32 v38, vcc, s2, v32
	s_movk_i32 s2, 0x4000
	s_nop 0
	v_addc_co_u32_e32 v39, vcc, 0, v33, vcc
	v_add_u32_e32 v178, s1, v182
	global_load_dwordx4 v[48:51], v[38:39], off
	global_load_dwordx4 v[60:63], v[34:35], off offset:16
	v_add_co_u32_e32 v34, vcc, s2, v32
	v_ashrrev_i32_e32 v179, 31, v178
	s_nop 0
	v_addc_co_u32_e32 v35, vcc, 0, v33, vcc
	s_mov_b64 s[2:3], 0x2200
	v_lshlrev_b64 v[180:181], 10, v[178:179]
	global_load_dwordx4 v[56:59], v[34:35], off
	global_load_dwordx4 v[52:55], v[36:37], off offset:16
	v_lshl_add_u64 v[36:37], v[32:33], 0, s[2:3]
	s_mov_b64 s[2:3], 0x4200
	v_lshl_add_u64 v[198:199], v[180:181], 0, v[176:177]
	v_lshl_add_u64 v[32:33], v[32:33], 0, s[2:3]
	v_lshl_add_u64 v[180:181], v[198:199], 2, s[12:13]
	v_lshl_add_u64 v[202:203], v[198:199], 2, s[12:13]
	global_load_dwordx4 v[44:47], v[38:39], off offset:512
	global_load_dwordx4 v[40:43], v[36:37], off offset:16
	s_nop 0
	global_load_dwordx4 v[36:39], v[34:35], off offset:512
	s_nop 0
	global_load_dwordx4 v[32:35], v[32:33], off offset:16
	s_nop 0
	global_load_dwordx4 v[212:215], v[202:203], off nt
	global_load_dwordx4 v[216:219], v[202:203], off offset:16 nt
	global_load_dwordx4 v[220:223], v[202:203], off offset:512 nt
	global_load_dwordx4 v[224:227], v[202:203], off offset:528 nt
	s_mov_b64 s[98:99], 0x10000
	v_lshl_add_u64 v[208:209], v[202:203], 0, s[98:99]
	global_load_dwordx4 v[228:231], v[208:209], off nt
	global_load_dwordx4 v[232:235], v[208:209], off offset:16 nt
	s_mov_b64 s[98:99], 0x10000
	v_lshl_add_u64 v[208:209], v[202:203], 0, s[98:99]
	global_load_dwordx4 v[236:239], v[208:209], off offset:512 nt
	global_load_dwordx4 v[240:243], v[208:209], off offset:528 nt
	s_mov_b64 s[98:99], 0x20000
	v_lshl_add_u64 v[208:209], v[202:203], 0, s[98:99]
	global_load_dwordx4 v[244:247], v[208:209], off nt
	global_load_dwordx4 v[248:251], v[208:209], off offset:16 nt
	s_waitcnt vmcnt(8)
	v_pk_fma_f32 v[190:191], v[152:153], v[60:61], v[216:217]
	v_pk_fma_f32 v[158:159], v[158:159], v[50:51], v[214:215]
	v_pk_fma_f32 v[156:157], v[156:157], v[48:49], v[212:213]
	v_mul_f32_e32 v153, v159, v159
	v_mul_f32_e32 v152, v157, v157
	v_pk_fma_f32 v[192:193], v[154:155], v[62:63], v[218:219]
	v_fmac_f32_e32 v152, v156, v156
	v_fmac_f32_e32 v153, v158, v158
	v_add_f32_e32 v152, v152, v153
	v_mul_f32_e32 v153, v191, v191
	v_mul_f32_e32 v154, v193, v193
	v_fmac_f32_e32 v153, v190, v190
	v_fmac_f32_e32 v154, v192, v192
	v_add_f32_e32 v153, v153, v154
	v_lshlrev_b64 v[194:195], 1, v[198:199]
	v_add_f32_e32 v200, v152, v153
	v_cvt_pk_bf16_f32 v152, v156, v157
	v_cvt_pk_bf16_f32 v153, v158, v159
	v_cvt_pk_bf16_f32 v154, v190, v191
	v_cvt_pk_bf16_f32 v155, v192, v193
	v_lshl_add_u64 v[196:197], s[74:75], 0, v[194:195]
	global_store_dwordx4 v[196:197], v[152:155], off
	s_nop 1
	v_pk_mul_f32 v[154:155], v[58:59], v[158:159]
	v_pk_mul_f32 v[152:153], v[56:57], v[156:157]
	v_pk_mul_f32 v[158:159], v[52:53], v[190:191]
	v_lshl_add_u64 v[190:191], s[76:77], 0, v[194:195]
	v_pk_mul_f32 v[156:157], v[54:55], v[192:193]
	v_cvt_pk_bf16_f32 v152, v152, v153
	v_cvt_pk_bf16_f32 v153, v154, v155
	v_cvt_pk_bf16_f32 v154, v158, v159
	s_nop 0
	v_cvt_pk_bf16_f32 v155, v156, v157
	global_store_dwordx4 v[190:191], v[152:155], off
	s_mov_b64 s[98:99], 0x20000
	v_lshl_add_u64 v[208:209], v[202:203], 0, s[98:99]
	global_load_dwordx4 v[212:215], v[208:209], off offset:512 nt
	global_load_dwordx4 v[216:219], v[208:209], off offset:528 nt
	s_nop 0
	s_waitcnt vmcnt(10)
	v_pk_fma_f32 v[152:153], v[144:145], v[40:41], v[224:225]
	s_waitcnt vmcnt(10)
	v_pk_fma_f32 v[150:151], v[150:151], v[46:47], v[222:223]
	v_pk_fma_f32 v[148:149], v[148:149], v[44:45], v[220:221]
	v_mul_f32_e32 v145, v151, v151
	v_mul_f32_e32 v144, v149, v149
	v_pk_fma_f32 v[154:155], v[146:147], v[42:43], v[226:227]
	v_fmac_f32_e32 v144, v148, v148
	v_fmac_f32_e32 v145, v150, v150
	v_add_f32_e32 v144, v144, v145
	v_mul_f32_e32 v145, v153, v153
	v_mul_f32_e32 v146, v155, v155
	v_fmac_f32_e32 v145, v152, v152
	v_fmac_f32_e32 v146, v154, v154
	v_add_f32_e32 v145, v145, v146
	v_add_f32_e32 v144, v144, v145
	v_add_f32_e32 v156, v200, v144
	v_cvt_pk_bf16_f32 v144, v148, v149
	v_cvt_pk_bf16_f32 v145, v150, v151
	v_cvt_pk_bf16_f32 v146, v152, v153
	v_cvt_pk_bf16_f32 v147, v154, v155
	global_store_dwordx4 v[196:197], v[144:147], off offset:256
	s_nop 1
	v_pk_mul_f32 v[144:145], v[36:37], v[148:149]
	v_pk_mul_f32 v[146:147], v[38:39], v[150:151]
	v_cvt_pk_bf16_f32 v144, v144, v145
	v_pk_mul_f32 v[148:149], v[34:35], v[154:155]
	v_cvt_pk_bf16_f32 v145, v146, v147
	v_pk_mul_f32 v[150:151], v[32:33], v[152:153]
	s_nop 0
	v_cvt_pk_bf16_f32 v146, v150, v151
	v_cvt_pk_bf16_f32 v147, v148, v149
	global_store_dwordx4 v[190:191], v[144:147], off offset:256
	s_nop 1
	v_and_b32_e32 v145, 64, v189
	v_xor_b32_e32 v144, 16, v189
	v_add_u32_e32 v145, 64, v145
	v_cmp_lt_i32_e32 vcc, v144, v145
	v_xor_b32_e32 v146, 32, v189
	s_nop 0
	v_cndmask_b32_e32 v144, v189, v144, vcc
	v_lshlrev_b32_e32 v148, 2, v144
	ds_bpermute_b32 v144, v148, v156
	v_cmp_lt_i32_e32 vcc, v146, v145
	s_waitcnt lgkmcnt(0)
	v_add_f32_e32 v144, v156, v144
	v_cndmask_b32_e32 v145, v189, v146, vcc
	v_lshlrev_b32_e32 v149, 2, v145
	ds_bpermute_b32 v145, v149, v144
	s_and_saveexec_b64 s[2:3], s[8:9]
	s_cbranch_execz .LBB0_622
	s_waitcnt lgkmcnt(0)
	v_add_f32_e32 v144, v144, v145
	ds_write_b32 v184, v144
.LBB0_622:
	s_or_b64 exec, exec, s[2:3]
	v_or_b32_e32 v144, 16, v178
	s_waitcnt lgkmcnt(0)
	v_ashrrev_i32_e32 v145, 31, v144
	v_lshlrev_b64 v[144:145], 10, v[144:145]
	v_lshl_add_u64 v[144:145], v[144:145], 0, v[176:177]
	v_lshl_add_u64 v[158:159], v[144:145], 2, s[12:13]
	s_mov_b64 s[98:99], 0x30000
	v_lshl_add_u64 v[208:209], v[202:203], 0, s[98:99]
	global_load_dwordx4 v[220:223], v[208:209], off nt
	global_load_dwordx4 v[224:227], v[208:209], off offset:16 nt
	v_lshlrev_b64 v[144:145], 1, v[144:145]
	v_lshl_add_u64 v[146:147], s[74:75], 0, v[144:145]
	v_lshl_add_u64 v[144:145], s[76:77], 0, v[144:145]
	s_waitcnt vmcnt(12)
	v_pk_fma_f32 v[152:153], v[142:143], v[50:51], v[230:231]
	v_pk_fma_f32 v[150:151], v[140:141], v[48:49], v[228:229]
	s_waitcnt vmcnt(12)
	v_pk_fma_f32 v[156:157], v[138:139], v[62:63], v[234:235]
	v_pk_fma_f32 v[154:155], v[136:137], v[60:61], v[232:233]
	v_cvt_pk_bf16_f32 v136, v150, v151
	v_cvt_pk_bf16_f32 v137, v152, v153
	v_pk_mul_f32 v[140:141], v[58:59], v[152:153]
	v_cvt_pk_bf16_f32 v138, v154, v155
	v_cvt_pk_bf16_f32 v139, v156, v157
	v_pk_mul_f32 v[142:143], v[56:57], v[150:151]
	v_pk_mul_f32 v[180:181], v[54:55], v[156:157]
	v_pk_mul_f32 v[190:191], v[52:53], v[154:155]
	global_store_dwordx4 v[146:147], v[136:139], off
	v_mul_f32_e32 v151, v151, v151
	v_mul_f32_e32 v153, v153, v153
	v_cvt_pk_bf16_f32 v136, v142, v143
	v_cvt_pk_bf16_f32 v137, v140, v141
	v_cvt_pk_bf16_f32 v138, v190, v191
	v_cvt_pk_bf16_f32 v139, v180, v181
	global_store_dwordx4 v[144:145], v[136:139], off
	s_mov_b64 s[98:99], 0x30000
	v_lshl_add_u64 v[208:209], v[202:203], 0, s[98:99]
	global_load_dwordx4 v[228:231], v[208:209], off offset:512 nt
	global_load_dwordx4 v[232:235], v[208:209], off offset:528 nt
	s_nop 0
	v_mul_f32_e32 v155, v155, v155
	v_mul_f32_e32 v157, v157, v157
	v_fmac_f32_e32 v151, v150, v150
	v_fmac_f32_e32 v153, v152, v152
	v_fmac_f32_e32 v155, v154, v154
	v_fmac_f32_e32 v157, v156, v156
	v_add_f32_e32 v150, v151, v153
	v_add_f32_e32 v151, v155, v157
	v_add_f32_e32 v150, v150, v151
	s_waitcnt vmcnt(14)
	v_pk_fma_f32 v[134:135], v[134:135], v[46:47], v[238:239]
	v_pk_fma_f32 v[132:133], v[132:133], v[44:45], v[236:237]
	s_waitcnt vmcnt(14)
	v_pk_fma_f32 v[136:137], v[130:131], v[42:43], v[242:243]
	v_pk_fma_f32 v[138:139], v[128:129], v[40:41], v[240:241]
	v_mul_f32_e32 v140, v133, v133
	v_mul_f32_e32 v141, v135, v135
	v_mul_f32_e32 v142, v139, v139
	v_mul_f32_e32 v143, v137, v137
	v_cvt_pk_bf16_f32 v128, v132, v133
	v_cvt_pk_bf16_f32 v129, v134, v135
	v_fmac_f32_e32 v140, v132, v132
	v_fmac_f32_e32 v141, v134, v134
	v_fmac_f32_e32 v142, v138, v138
	v_fmac_f32_e32 v143, v136, v136
	v_cvt_pk_bf16_f32 v130, v138, v139
	v_cvt_pk_bf16_f32 v131, v136, v137
	global_store_dwordx4 v[146:147], v[128:131], off offset:256
	v_pk_mul_f32 v[134:135], v[38:39], v[134:135]
	v_pk_mul_f32 v[136:137], v[34:35], v[136:137]
	v_add_f32_e32 v128, v140, v141
	v_add_f32_e32 v129, v142, v143
	v_add_f32_e32 v128, v128, v129
	v_add_f32_e32 v131, v150, v128
	ds_bpermute_b32 v140, v148, v131
	v_pk_mul_f32 v[128:129], v[36:37], v[132:133]
	v_pk_mul_f32 v[132:133], v[32:33], v[138:139]
	v_cvt_pk_bf16_f32 v130, v128, v129
	s_waitcnt lgkmcnt(0)
	v_add_f32_e32 v128, v131, v140
	ds_bpermute_b32 v129, v149, v128
	v_cvt_pk_bf16_f32 v131, v134, v135
	v_cvt_pk_bf16_f32 v132, v132, v133
	v_cvt_pk_bf16_f32 v133, v136, v137
	global_store_dwordx4 v[144:145], v[130:133], off offset:256
	s_and_saveexec_b64 s[2:3], s[8:9]
	s_cbranch_execz .LBB0_624
	s_waitcnt lgkmcnt(0)
	v_add_f32_e32 v128, v128, v129
	ds_write_b32 v184, v128 offset:256
.LBB0_624:
	s_or_b64 exec, exec, s[2:3]
	v_or_b32_e32 v128, 32, v178
	s_waitcnt lgkmcnt(0)
	v_ashrrev_i32_e32 v129, 31, v128
	v_lshlrev_b64 v[128:129], 10, v[128:129]
	v_lshl_add_u64 v[128:129], v[128:129], 0, v[176:177]
	v_lshl_add_u64 v[140:141], v[128:129], 2, s[12:13]
	s_mov_b64 s[98:99], 0x80000
	v_lshl_add_u64 v[208:209], v[202:203], 0, s[98:99]
	global_load_dwordx4 v[236:239], v[208:209], off nt
	global_load_dwordx4 v[240:243], v[208:209], off offset:16 nt
	v_lshlrev_b64 v[128:129], 1, v[128:129]
	v_lshl_add_u64 v[130:131], s[74:75], 0, v[128:129]
	v_lshl_add_u64 v[128:129], s[76:77], 0, v[128:129]
	s_waitcnt vmcnt(16)
	v_pk_fma_f32 v[134:135], v[126:127], v[50:51], v[246:247]
	v_pk_fma_f32 v[132:133], v[124:125], v[48:49], v[244:245]
	s_waitcnt vmcnt(16)
	v_pk_fma_f32 v[138:139], v[122:123], v[62:63], v[250:251]
	v_pk_fma_f32 v[136:137], v[120:121], v[60:61], v[248:249]
	v_cvt_pk_bf16_f32 v120, v132, v133
	v_cvt_pk_bf16_f32 v121, v134, v135
	v_pk_mul_f32 v[124:125], v[58:59], v[134:135]
	v_cvt_pk_bf16_f32 v122, v136, v137
	v_cvt_pk_bf16_f32 v123, v138, v139
	v_pk_mul_f32 v[126:127], v[56:57], v[132:133]
	v_pk_mul_f32 v[142:143], v[54:55], v[138:139]
	v_pk_mul_f32 v[144:145], v[52:53], v[136:137]
	global_store_dwordx4 v[130:131], v[120:123], off
	v_mul_f32_e32 v133, v133, v133
	v_mul_f32_e32 v135, v135, v135
	v_cvt_pk_bf16_f32 v120, v126, v127
	v_cvt_pk_bf16_f32 v121, v124, v125
	v_cvt_pk_bf16_f32 v122, v144, v145
	v_cvt_pk_bf16_f32 v123, v142, v143
	global_store_dwordx4 v[128:129], v[120:123], off
	s_mov_b64 s[98:99], 0x80000
	v_lshl_add_u64 v[208:209], v[202:203], 0, s[98:99]
	global_load_dwordx4 v[244:247], v[208:209], off offset:512 nt
	global_load_dwordx4 v[248:251], v[208:209], off offset:528 nt
	s_nop 0
	v_mul_f32_e32 v137, v137, v137
	v_mul_f32_e32 v139, v139, v139
	v_fmac_f32_e32 v133, v132, v132
	v_fmac_f32_e32 v135, v134, v134
	v_fmac_f32_e32 v137, v136, v136
	v_fmac_f32_e32 v139, v138, v138
	v_add_f32_e32 v132, v133, v135
	v_add_f32_e32 v133, v137, v139
	v_add_f32_e32 v132, v132, v133
	s_waitcnt vmcnt(16)
	v_pk_fma_f32 v[118:119], v[118:119], v[46:47], v[214:215]
	v_pk_fma_f32 v[116:117], v[116:117], v[44:45], v[212:213]
	s_waitcnt vmcnt(16)
	v_pk_fma_f32 v[120:121], v[114:115], v[42:43], v[218:219]
	v_pk_fma_f32 v[122:123], v[112:113], v[40:41], v[216:217]
	v_mul_f32_e32 v124, v117, v117
	v_mul_f32_e32 v125, v119, v119
	v_mul_f32_e32 v126, v123, v123
	v_mul_f32_e32 v127, v121, v121
	v_cvt_pk_bf16_f32 v112, v116, v117
	v_cvt_pk_bf16_f32 v113, v118, v119
	v_fmac_f32_e32 v124, v116, v116
	v_fmac_f32_e32 v125, v118, v118
	v_fmac_f32_e32 v126, v122, v122
	v_fmac_f32_e32 v127, v120, v120
	v_cvt_pk_bf16_f32 v114, v122, v123
	v_cvt_pk_bf16_f32 v115, v120, v121
	global_store_dwordx4 v[130:131], v[112:115], off offset:256
	v_pk_mul_f32 v[118:119], v[38:39], v[118:119]
	v_pk_mul_f32 v[120:121], v[34:35], v[120:121]
	v_add_f32_e32 v112, v124, v125
	v_add_f32_e32 v113, v126, v127
	v_add_f32_e32 v112, v112, v113
	v_add_f32_e32 v115, v132, v112
	ds_bpermute_b32 v124, v148, v115
	v_pk_mul_f32 v[112:113], v[36:37], v[116:117]
	v_pk_mul_f32 v[116:117], v[32:33], v[122:123]
	v_cvt_pk_bf16_f32 v114, v112, v113
	s_waitcnt lgkmcnt(0)
	v_add_f32_e32 v112, v115, v124
	ds_bpermute_b32 v113, v149, v112
	v_cvt_pk_bf16_f32 v115, v118, v119
	v_cvt_pk_bf16_f32 v116, v116, v117
	v_cvt_pk_bf16_f32 v117, v120, v121
	global_store_dwordx4 v[128:129], v[114:117], off offset:256
	s_and_saveexec_b64 s[2:3], s[8:9]
	s_cbranch_execz .LBB0_626
	s_waitcnt lgkmcnt(0)
	v_add_f32_e32 v112, v112, v113
	ds_write_b32 v184, v112 offset:512
.LBB0_626:
	s_or_b64 exec, exec, s[2:3]
	v_or_b32_e32 v112, 48, v178
	s_waitcnt lgkmcnt(0)
	v_ashrrev_i32_e32 v113, 31, v112
	v_lshlrev_b64 v[112:113], 10, v[112:113]
	v_lshl_add_u64 v[112:113], v[112:113], 0, v[176:177]
	v_lshl_add_u64 v[124:125], v[112:113], 2, s[12:13]
	s_mov_b64 s[98:99], 0x90000
	v_lshl_add_u64 v[208:209], v[202:203], 0, s[98:99]
	global_load_dwordx4 v[212:215], v[208:209], off nt
	global_load_dwordx4 v[216:219], v[208:209], off offset:16 nt
	v_lshlrev_b64 v[112:113], 1, v[112:113]
	v_lshl_add_u64 v[114:115], s[74:75], 0, v[112:113]
	v_lshl_add_u64 v[112:113], s[76:77], 0, v[112:113]
	s_waitcnt vmcnt(16)
	v_pk_fma_f32 v[118:119], v[110:111], v[50:51], v[222:223]
	v_pk_fma_f32 v[116:117], v[108:109], v[48:49], v[220:221]
	s_waitcnt vmcnt(16)
	v_pk_fma_f32 v[122:123], v[106:107], v[62:63], v[226:227]
	v_pk_fma_f32 v[120:121], v[104:105], v[60:61], v[224:225]
	v_cvt_pk_bf16_f32 v104, v116, v117
	v_cvt_pk_bf16_f32 v105, v118, v119
	v_pk_mul_f32 v[108:109], v[58:59], v[118:119]
	v_cvt_pk_bf16_f32 v106, v120, v121
	v_cvt_pk_bf16_f32 v107, v122, v123
	v_pk_mul_f32 v[110:111], v[56:57], v[116:117]
	v_pk_mul_f32 v[126:127], v[54:55], v[122:123]
	v_pk_mul_f32 v[128:129], v[52:53], v[120:121]
	global_store_dwordx4 v[114:115], v[104:107], off
	v_mul_f32_e32 v117, v117, v117
	v_mul_f32_e32 v119, v119, v119
	v_cvt_pk_bf16_f32 v104, v110, v111
	v_cvt_pk_bf16_f32 v105, v108, v109
	v_cvt_pk_bf16_f32 v106, v128, v129
	v_cvt_pk_bf16_f32 v107, v126, v127
	global_store_dwordx4 v[112:113], v[104:107], off
	s_mov_b64 s[98:99], 0x90000
	v_lshl_add_u64 v[208:209], v[202:203], 0, s[98:99]
	global_load_dwordx4 v[220:223], v[208:209], off offset:512 nt
	global_load_dwordx4 v[224:227], v[208:209], off offset:528 nt
	s_nop 0
	v_mul_f32_e32 v121, v121, v121
	v_mul_f32_e32 v123, v123, v123
	v_fmac_f32_e32 v117, v116, v116
	v_fmac_f32_e32 v119, v118, v118
	v_fmac_f32_e32 v121, v120, v120
	v_fmac_f32_e32 v123, v122, v122
	v_add_f32_e32 v116, v117, v119
	v_add_f32_e32 v117, v121, v123
	v_add_f32_e32 v116, v116, v117
	s_waitcnt vmcnt(16)
	v_pk_fma_f32 v[102:103], v[102:103], v[46:47], v[230:231]
	v_pk_fma_f32 v[100:101], v[100:101], v[44:45], v[228:229]
	s_waitcnt vmcnt(16)
	v_pk_fma_f32 v[104:105], v[98:99], v[42:43], v[234:235]
	v_pk_fma_f32 v[106:107], v[96:97], v[40:41], v[232:233]
	v_mul_f32_e32 v108, v101, v101
	v_mul_f32_e32 v109, v103, v103
	v_mul_f32_e32 v110, v107, v107
	v_mul_f32_e32 v111, v105, v105
	v_cvt_pk_bf16_f32 v96, v100, v101
	v_cvt_pk_bf16_f32 v97, v102, v103
	v_fmac_f32_e32 v108, v100, v100
	v_fmac_f32_e32 v109, v102, v102
	v_fmac_f32_e32 v110, v106, v106
	v_fmac_f32_e32 v111, v104, v104
	v_cvt_pk_bf16_f32 v98, v106, v107
	v_cvt_pk_bf16_f32 v99, v104, v105
	global_store_dwordx4 v[114:115], v[96:99], off offset:256
	v_pk_mul_f32 v[102:103], v[38:39], v[102:103]
	v_pk_mul_f32 v[104:105], v[34:35], v[104:105]
	v_add_f32_e32 v96, v108, v109
	v_add_f32_e32 v97, v110, v111
	v_add_f32_e32 v96, v96, v97
	v_add_f32_e32 v99, v116, v96
	ds_bpermute_b32 v108, v148, v99
	v_pk_mul_f32 v[96:97], v[36:37], v[100:101]
	v_pk_mul_f32 v[100:101], v[32:33], v[106:107]
	v_cvt_pk_bf16_f32 v98, v96, v97
	s_waitcnt lgkmcnt(0)
	v_add_f32_e32 v96, v99, v108
	ds_bpermute_b32 v97, v149, v96
	v_cvt_pk_bf16_f32 v99, v102, v103
	v_cvt_pk_bf16_f32 v100, v100, v101
	v_cvt_pk_bf16_f32 v101, v104, v105
	global_store_dwordx4 v[112:113], v[98:101], off offset:256
	s_and_saveexec_b64 s[2:3], s[8:9]
	s_cbranch_execz .LBB0_628
	s_waitcnt lgkmcnt(0)
	v_add_f32_e32 v96, v96, v97
	ds_write_b32 v184, v96 offset:768
.LBB0_628:
	s_or_b64 exec, exec, s[2:3]
	s_waitcnt lgkmcnt(0)
	v_lshlrev_b64 v[96:97], 10, v[178:179]
	v_lshl_add_u64 v[96:97], v[96:97], 0, v[176:177]
	s_mov_b64 s[2:3], 0x20000
	v_lshl_add_u64 v[98:99], v[96:97], 0, s[2:3]
	v_lshl_add_u64 v[110:111], v[98:99], 2, s[12:13]
	s_mov_b64 s[98:99], 0xa0000
	v_lshl_add_u64 v[208:209], v[202:203], 0, s[98:99]
	global_load_dwordx4 v[228:231], v[208:209], off nt
	global_load_dwordx4 v[232:235], v[208:209], off offset:16 nt
	v_lshlrev_b64 v[98:99], 1, v[98:99]
	v_lshl_add_u64 v[100:101], s[74:75], 0, v[98:99]
	v_lshl_add_u64 v[98:99], s[76:77], 0, v[98:99]
	s_waitcnt vmcnt(16)
	v_pk_fma_f32 v[104:105], v[94:95], v[50:51], v[238:239]
	v_pk_fma_f32 v[102:103], v[92:93], v[48:49], v[236:237]
	s_waitcnt vmcnt(16)
	v_pk_fma_f32 v[108:109], v[90:91], v[62:63], v[242:243]
	v_pk_fma_f32 v[106:107], v[88:89], v[60:61], v[240:241]
	v_cvt_pk_bf16_f32 v88, v102, v103
	v_cvt_pk_bf16_f32 v89, v104, v105
	v_pk_mul_f32 v[92:93], v[58:59], v[104:105]
	v_cvt_pk_bf16_f32 v90, v106, v107
	v_cvt_pk_bf16_f32 v91, v108, v109
	v_pk_mul_f32 v[94:95], v[56:57], v[102:103]
	v_pk_mul_f32 v[112:113], v[54:55], v[108:109]
	v_pk_mul_f32 v[114:115], v[52:53], v[106:107]
	global_store_dwordx4 v[100:101], v[88:91], off
	v_mul_f32_e32 v103, v103, v103
	v_mul_f32_e32 v105, v105, v105
	v_cvt_pk_bf16_f32 v88, v94, v95
	v_cvt_pk_bf16_f32 v89, v92, v93
	v_cvt_pk_bf16_f32 v90, v114, v115
	v_cvt_pk_bf16_f32 v91, v112, v113
	global_store_dwordx4 v[98:99], v[88:91], off
	s_mov_b64 s[98:99], 0xa0000
	v_lshl_add_u64 v[208:209], v[202:203], 0, s[98:99]
	global_load_dwordx4 v[236:239], v[208:209], off offset:512 nt
	global_load_dwordx4 v[240:243], v[208:209], off offset:528 nt
	s_nop 0
	v_mul_f32_e32 v107, v107, v107
	v_mul_f32_e32 v109, v109, v109
	v_fmac_f32_e32 v103, v102, v102
	v_fmac_f32_e32 v105, v104, v104
	v_fmac_f32_e32 v107, v106, v106
	v_fmac_f32_e32 v109, v108, v108
	v_add_f32_e32 v102, v103, v105
	v_add_f32_e32 v103, v107, v109
	v_add_f32_e32 v102, v102, v103
	s_waitcnt vmcnt(16)
	v_pk_fma_f32 v[86:87], v[86:87], v[46:47], v[246:247]
	v_pk_fma_f32 v[84:85], v[84:85], v[44:45], v[244:245]
	s_waitcnt vmcnt(16)
	v_pk_fma_f32 v[88:89], v[82:83], v[42:43], v[250:251]
	v_pk_fma_f32 v[90:91], v[80:81], v[40:41], v[248:249]
	v_mul_f32_e32 v92, v85, v85
	v_mul_f32_e32 v93, v87, v87
	v_mul_f32_e32 v94, v91, v91
	v_mul_f32_e32 v95, v89, v89
	v_cvt_pk_bf16_f32 v80, v84, v85
	v_cvt_pk_bf16_f32 v81, v86, v87
	v_fmac_f32_e32 v92, v84, v84
	v_fmac_f32_e32 v93, v86, v86
	v_fmac_f32_e32 v94, v90, v90
	v_fmac_f32_e32 v95, v88, v88
	v_cvt_pk_bf16_f32 v82, v90, v91
	v_cvt_pk_bf16_f32 v83, v88, v89
	global_store_dwordx4 v[100:101], v[80:83], off offset:256
	v_pk_mul_f32 v[86:87], v[38:39], v[86:87]
	v_pk_mul_f32 v[88:89], v[34:35], v[88:89]
	v_add_f32_e32 v80, v92, v93
	v_add_f32_e32 v81, v94, v95
	v_add_f32_e32 v80, v80, v81
	v_add_f32_e32 v83, v102, v80
	ds_bpermute_b32 v92, v148, v83
	v_pk_mul_f32 v[80:81], v[36:37], v[84:85]
	v_pk_mul_f32 v[84:85], v[32:33], v[90:91]
	v_cvt_pk_bf16_f32 v82, v80, v81
	s_waitcnt lgkmcnt(0)
	v_add_f32_e32 v80, v83, v92
	ds_bpermute_b32 v81, v149, v80
	v_cvt_pk_bf16_f32 v83, v86, v87
	v_cvt_pk_bf16_f32 v84, v84, v85
	v_cvt_pk_bf16_f32 v85, v88, v89
	global_store_dwordx4 v[98:99], v[82:85], off offset:256
	s_and_saveexec_b64 s[2:3], s[8:9]
	s_cbranch_execz .LBB0_630
	s_waitcnt lgkmcnt(0)
	v_add_f32_e32 v80, v80, v81
	ds_write_b32 v184, v80 offset:2048
.LBB0_630:
	s_or_b64 exec, exec, s[2:3]
	s_mov_b64 s[2:3], 0x24000
	s_waitcnt lgkmcnt(0)
	v_lshl_add_u64 v[80:81], v[96:97], 0, s[2:3]
	v_lshl_add_u64 v[92:93], v[80:81], 2, s[12:13]
	s_mov_b64 s[98:99], 0xb0000
	v_lshl_add_u64 v[208:209], v[202:203], 0, s[98:99]
	global_load_dwordx4 v[244:247], v[208:209], off nt
	global_load_dwordx4 v[248:251], v[208:209], off offset:16 nt
	v_lshlrev_b64 v[80:81], 1, v[80:81]
	v_lshl_add_u64 v[82:83], s[74:75], 0, v[80:81]
	v_lshl_add_u64 v[80:81], s[76:77], 0, v[80:81]
	s_waitcnt vmcnt(16)
	v_pk_fma_f32 v[86:87], v[78:79], v[50:51], v[214:215]
	v_pk_fma_f32 v[84:85], v[76:77], v[48:49], v[212:213]
	s_waitcnt vmcnt(16)
	v_pk_fma_f32 v[90:91], v[74:75], v[62:63], v[218:219]
	v_pk_fma_f32 v[88:89], v[72:73], v[60:61], v[216:217]
	v_cvt_pk_bf16_f32 v72, v84, v85
	v_cvt_pk_bf16_f32 v73, v86, v87
	v_pk_mul_f32 v[76:77], v[58:59], v[86:87]
	v_cvt_pk_bf16_f32 v74, v88, v89
	v_cvt_pk_bf16_f32 v75, v90, v91
	v_pk_mul_f32 v[78:79], v[56:57], v[84:85]
	v_pk_mul_f32 v[94:95], v[54:55], v[90:91]
	v_pk_mul_f32 v[96:97], v[52:53], v[88:89]
	global_store_dwordx4 v[82:83], v[72:75], off
	v_mul_f32_e32 v85, v85, v85
	v_mul_f32_e32 v87, v87, v87
	v_cvt_pk_bf16_f32 v72, v78, v79
	v_cvt_pk_bf16_f32 v73, v76, v77
	v_cvt_pk_bf16_f32 v74, v96, v97
	v_cvt_pk_bf16_f32 v75, v94, v95
	global_store_dwordx4 v[80:81], v[72:75], off
	s_mov_b64 s[98:99], 0xb0000
	v_lshl_add_u64 v[208:209], v[202:203], 0, s[98:99]
	global_load_dwordx4 v[212:215], v[208:209], off offset:512 nt
	global_load_dwordx4 v[216:219], v[208:209], off offset:528 nt
	s_nop 0
	v_mul_f32_e32 v89, v89, v89
	v_mul_f32_e32 v91, v91, v91
	v_fmac_f32_e32 v85, v84, v84
	v_fmac_f32_e32 v87, v86, v86
	v_fmac_f32_e32 v89, v88, v88
	v_fmac_f32_e32 v91, v90, v90
	v_add_f32_e32 v84, v85, v87
	v_add_f32_e32 v85, v89, v91
	v_add_f32_e32 v84, v84, v85
	s_waitcnt vmcnt(16)
	v_pk_fma_f32 v[70:71], v[70:71], v[46:47], v[222:223]
	v_pk_fma_f32 v[68:69], v[68:69], v[44:45], v[220:221]
	s_waitcnt vmcnt(16)
	v_pk_fma_f32 v[72:73], v[66:67], v[42:43], v[226:227]
	v_pk_fma_f32 v[74:75], v[64:65], v[40:41], v[224:225]
	v_mul_f32_e32 v76, v69, v69
	v_mul_f32_e32 v77, v71, v71
	v_mul_f32_e32 v78, v75, v75
	v_mul_f32_e32 v79, v73, v73
	v_cvt_pk_bf16_f32 v64, v68, v69
	v_cvt_pk_bf16_f32 v65, v70, v71
	v_fmac_f32_e32 v76, v68, v68
	v_fmac_f32_e32 v77, v70, v70
	v_fmac_f32_e32 v78, v74, v74
	v_fmac_f32_e32 v79, v72, v72
	v_cvt_pk_bf16_f32 v66, v74, v75
	v_cvt_pk_bf16_f32 v67, v72, v73
	global_store_dwordx4 v[82:83], v[64:67], off offset:256
	v_pk_mul_f32 v[70:71], v[38:39], v[70:71]
	v_pk_mul_f32 v[72:73], v[34:35], v[72:73]
	v_add_f32_e32 v64, v76, v77
	v_add_f32_e32 v65, v78, v79
	v_add_f32_e32 v64, v64, v65
	v_add_f32_e32 v67, v84, v64
	ds_bpermute_b32 v76, v148, v67
	v_pk_mul_f32 v[64:65], v[36:37], v[68:69]
	v_pk_mul_f32 v[68:69], v[32:33], v[74:75]
	v_cvt_pk_bf16_f32 v66, v64, v65
	s_waitcnt lgkmcnt(0)
	v_add_f32_e32 v64, v67, v76
	ds_bpermute_b32 v65, v149, v64
	v_cvt_pk_bf16_f32 v67, v70, v71
	v_cvt_pk_bf16_f32 v68, v68, v69
	v_cvt_pk_bf16_f32 v69, v72, v73
	global_store_dwordx4 v[80:81], v[66:69], off offset:256
	s_and_saveexec_b64 s[2:3], s[8:9]
	s_cbranch_execz .LBB0_632
	s_waitcnt lgkmcnt(0)
	v_add_f32_e32 v64, v64, v65
	ds_write_b32 v184, v64 offset:2304
.LBB0_632:
	s_or_b64 exec, exec, s[2:3]
	s_waitcnt lgkmcnt(0)
	v_lshlrev_b64 v[64:65], 10, v[178:179]
	v_lshl_add_u64 v[64:65], v[64:65], 0, v[176:177]
	s_mov_b64 s[2:3], 0x28000
	v_lshl_add_u64 v[66:67], v[64:65], 0, s[2:3]
	v_lshl_add_u64 v[78:79], v[66:67], 2, s[12:13]
	v_lshlrev_b64 v[66:67], 1, v[66:67]
	v_lshl_add_u64 v[68:69], s[74:75], 0, v[66:67]
	v_lshl_add_u64 v[66:67], s[76:77], 0, v[66:67]
	s_waitcnt vmcnt(14)
	v_pk_fma_f32 v[72:73], v[30:31], v[50:51], v[230:231]
	v_pk_fma_f32 v[70:71], v[28:29], v[48:49], v[228:229]
	s_waitcnt vmcnt(14)
	v_pk_fma_f32 v[76:77], v[26:27], v[62:63], v[234:235]
	v_pk_fma_f32 v[74:75], v[24:25], v[60:61], v[232:233]
	v_cvt_pk_bf16_f32 v24, v70, v71
	v_cvt_pk_bf16_f32 v25, v72, v73
	v_pk_mul_f32 v[28:29], v[58:59], v[72:73]
	v_cvt_pk_bf16_f32 v26, v74, v75
	v_cvt_pk_bf16_f32 v27, v76, v77
	v_pk_mul_f32 v[30:31], v[56:57], v[70:71]
	v_pk_mul_f32 v[80:81], v[54:55], v[76:77]
	v_pk_mul_f32 v[82:83], v[52:53], v[74:75]
	global_store_dwordx4 v[68:69], v[24:27], off
	v_mul_f32_e32 v71, v71, v71
	v_mul_f32_e32 v73, v73, v73
	v_cvt_pk_bf16_f32 v24, v30, v31
	v_cvt_pk_bf16_f32 v25, v28, v29
	v_cvt_pk_bf16_f32 v26, v82, v83
	v_cvt_pk_bf16_f32 v27, v80, v81
	global_store_dwordx4 v[66:67], v[24:27], off
	s_nop 0
	v_mul_f32_e32 v75, v75, v75
	v_mul_f32_e32 v77, v77, v77
	v_fmac_f32_e32 v71, v70, v70
	v_fmac_f32_e32 v73, v72, v72
	v_fmac_f32_e32 v75, v74, v74
	v_fmac_f32_e32 v77, v76, v76
	v_add_f32_e32 v70, v71, v73
	v_add_f32_e32 v71, v75, v77
	v_add_f32_e32 v70, v70, v71
	s_waitcnt vmcnt(12)
	v_pk_fma_f32 v[22:23], v[22:23], v[46:47], v[238:239]
	v_pk_fma_f32 v[20:21], v[20:21], v[44:45], v[236:237]
	s_waitcnt vmcnt(12)
	v_pk_fma_f32 v[24:25], v[18:19], v[42:43], v[242:243]
	v_pk_fma_f32 v[26:27], v[16:17], v[40:41], v[240:241]
	v_mul_f32_e32 v28, v21, v21
	v_mul_f32_e32 v29, v23, v23
	v_mul_f32_e32 v30, v27, v27
	v_mul_f32_e32 v31, v25, v25
	v_cvt_pk_bf16_f32 v16, v20, v21
	v_cvt_pk_bf16_f32 v17, v22, v23
	v_fmac_f32_e32 v28, v20, v20
	v_fmac_f32_e32 v29, v22, v22
	v_fmac_f32_e32 v30, v26, v26
	v_fmac_f32_e32 v31, v24, v24
	v_cvt_pk_bf16_f32 v18, v26, v27
	v_cvt_pk_bf16_f32 v19, v24, v25
	global_store_dwordx4 v[68:69], v[16:19], off offset:256
	v_pk_mul_f32 v[22:23], v[38:39], v[22:23]
	v_pk_mul_f32 v[24:25], v[34:35], v[24:25]
	v_add_f32_e32 v16, v28, v29
	v_add_f32_e32 v17, v30, v31
	v_add_f32_e32 v16, v16, v17
	v_add_f32_e32 v19, v70, v16
	ds_bpermute_b32 v28, v148, v19
	v_pk_mul_f32 v[16:17], v[36:37], v[20:21]
	v_pk_mul_f32 v[20:21], v[32:33], v[26:27]
	v_cvt_pk_bf16_f32 v18, v16, v17
	s_waitcnt lgkmcnt(0)
	v_add_f32_e32 v16, v19, v28
	ds_bpermute_b32 v17, v149, v16
	v_cvt_pk_bf16_f32 v19, v22, v23
	v_cvt_pk_bf16_f32 v20, v20, v21
	v_cvt_pk_bf16_f32 v21, v24, v25
	global_store_dwordx4 v[66:67], v[18:21], off offset:256
	s_and_saveexec_b64 s[2:3], s[8:9]
	s_cbranch_execz .LBB0_634
	s_waitcnt lgkmcnt(0)
	v_add_f32_e32 v16, v16, v17
	ds_write_b32 v184, v16 offset:2560
.LBB0_634:
	s_or_b64 exec, exec, s[2:3]
	s_mov_b64 s[2:3], 0x2c000
	s_waitcnt lgkmcnt(0)
	v_lshl_add_u64 v[16:17], v[64:65], 0, s[2:3]
	v_lshl_add_u64 v[28:29], v[16:17], 2, s[12:13]
	v_lshlrev_b64 v[16:17], 1, v[16:17]
	v_lshl_add_u64 v[18:19], s[74:75], 0, v[16:17]
	v_lshl_add_u64 v[16:17], s[76:77], 0, v[16:17]
	s_waitcnt vmcnt(10)
	v_pk_fma_f32 v[22:23], v[14:15], v[50:51], v[246:247]
	v_pk_fma_f32 v[20:21], v[12:13], v[48:49], v[244:245]
	s_waitcnt vmcnt(10)
	v_pk_fma_f32 v[26:27], v[10:11], v[62:63], v[250:251]
	v_pk_fma_f32 v[24:25], v[8:9], v[60:61], v[248:249]
	v_cvt_pk_bf16_f32 v8, v20, v21
	v_cvt_pk_bf16_f32 v9, v22, v23
	v_pk_mul_f32 v[12:13], v[58:59], v[22:23]
	v_cvt_pk_bf16_f32 v10, v24, v25
	v_cvt_pk_bf16_f32 v11, v26, v27
	v_pk_mul_f32 v[14:15], v[56:57], v[20:21]
	v_pk_mul_f32 v[30:31], v[54:55], v[26:27]
	v_pk_mul_f32 v[48:49], v[52:53], v[24:25]
	global_store_dwordx4 v[18:19], v[8:11], off
	v_mul_f32_e32 v21, v21, v21
	v_mul_f32_e32 v23, v23, v23
	v_cvt_pk_bf16_f32 v8, v14, v15
	v_cvt_pk_bf16_f32 v9, v12, v13
	v_cvt_pk_bf16_f32 v10, v48, v49
	v_cvt_pk_bf16_f32 v11, v30, v31
	global_store_dwordx4 v[16:17], v[8:11], off
	s_nop 0
	v_mul_f32_e32 v25, v25, v25
	v_mul_f32_e32 v27, v27, v27
	v_fmac_f32_e32 v21, v20, v20
	v_fmac_f32_e32 v23, v22, v22
	v_fmac_f32_e32 v25, v24, v24
	v_fmac_f32_e32 v27, v26, v26
	v_add_f32_e32 v20, v21, v23
	v_add_f32_e32 v21, v25, v27
	v_add_f32_e32 v20, v20, v21
	s_waitcnt vmcnt(8)
	v_pk_fma_f32 v[6:7], v[6:7], v[46:47], v[214:215]
	v_pk_fma_f32 v[4:5], v[4:5], v[44:45], v[212:213]
	s_waitcnt vmcnt(8)
	v_pk_fma_f32 v[8:9], v[2:3], v[42:43], v[218:219]
	v_pk_fma_f32 v[10:11], v[0:1], v[40:41], v[216:217]
	v_mul_f32_e32 v12, v5, v5
	v_mul_f32_e32 v13, v7, v7
	v_mul_f32_e32 v14, v11, v11
	v_mul_f32_e32 v15, v9, v9
	v_cvt_pk_bf16_f32 v0, v4, v5
	v_cvt_pk_bf16_f32 v1, v6, v7
	v_fmac_f32_e32 v12, v4, v4
	v_fmac_f32_e32 v13, v6, v6
	v_fmac_f32_e32 v14, v10, v10
	v_fmac_f32_e32 v15, v8, v8
	v_cvt_pk_bf16_f32 v2, v10, v11
	v_cvt_pk_bf16_f32 v3, v8, v9
	global_store_dwordx4 v[18:19], v[0:3], off offset:256
	v_pk_mul_f32 v[6:7], v[38:39], v[6:7]
	v_pk_mul_f32 v[8:9], v[34:35], v[8:9]
	v_add_f32_e32 v0, v12, v13
	v_add_f32_e32 v1, v14, v15
	v_add_f32_e32 v0, v0, v1
	v_add_f32_e32 v3, v20, v0
	ds_bpermute_b32 v12, v148, v3
	v_pk_mul_f32 v[0:1], v[36:37], v[4:5]
	v_pk_mul_f32 v[4:5], v[32:33], v[10:11]
	v_cvt_pk_bf16_f32 v2, v0, v1
	s_waitcnt lgkmcnt(0)
	v_add_f32_e32 v0, v3, v12
	ds_bpermute_b32 v1, v149, v0
	v_cvt_pk_bf16_f32 v3, v6, v7
	v_cvt_pk_bf16_f32 v4, v4, v5
	v_cvt_pk_bf16_f32 v5, v8, v9
	global_store_dwordx4 v[16:17], v[2:5], off offset:256
	s_and_saveexec_b64 s[2:3], s[8:9]
	s_cbranch_execz .LBB0_636
	s_waitcnt lgkmcnt(0)
	v_add_f32_e32 v0, v0, v1
	ds_write_b32 v184, v0 offset:2816

.Lnowb_6:
	s_waitcnt lgkmcnt(0)
	s_waitcnt vmcnt(0)
	v_mbcnt_lo_u32_b32 v1, s4, 0
	v_mbcnt_hi_u32_b32 v1, s5, v1
	v_cmp_eq_u32_e32 vcc, 0, v1
	s_and_saveexec_b64 s[6:7], vcc
	s_cbranch_execz .LBB0_1119
	s_bcnt1_i32_b64 s4, s[4:5]
	v_mov_b32_e32 v2, 0x3000
	v_mov_b32_e32 v3, s4
	global_atomic_add v2, v2, v3, s[62:63] offset:1024 sc0

.LBB0_1214:
	s_andn2_saveexec_b64 s[6:7], s[6:7]
	s_cbranch_execz .LBB0_1234
	s_mov_b64 s[6:7], exec
	v_cmp_eq_u32_e32 vcc, 1, v0
	s_cbranch_vccnz .Lnowb_7
	buffer_wbl2 sc1
.Lnowb_7:
	s_waitcnt lgkmcnt(0)
	s_waitcnt vmcnt(0)
	v_mbcnt_lo_u32_b32 v1, s6, 0
	v_mbcnt_hi_u32_b32 v1, s7, v1
	v_cmp_eq_u32_e32 vcc, 0, v1
	s_and_saveexec_b64 s[8:9], vcc
	s_cbranch_execz .LBB0_1217
	s_bcnt1_i32_b64 s6, s[6:7]
	v_mov_b32_e32 v2, 0x3000
	v_mov_b32_e32 v3, s6
	global_atomic_add v2, v2, v3, s[62:63] offset:1024 sc0

	.amdhsa_kernel _Z9hymba_fwd4Args
		.amdhsa_group_segment_fixed_size 0
		.amdhsa_private_segment_fixed_size 0
		.amdhsa_kernarg_size 496
		.amdhsa_user_sgpr_count 2
		.amdhsa_user_sgpr_dispatch_ptr 0
		.amdhsa_user_sgpr_queue_ptr 0
		.amdhsa_user_sgpr_kernarg_segment_ptr 1
		.amdhsa_user_sgpr_dispatch_id 0
		.amdhsa_user_sgpr_kernarg_preload_length 0
		.amdhsa_user_sgpr_kernarg_preload_offset 0
		.amdhsa_user_sgpr_private_segment_size 0
		.amdhsa_uses_dynamic_stack 0
		.amdhsa_enable_private_segment 0
		.amdhsa_system_sgpr_workgroup_id_x 1
		.amdhsa_system_sgpr_workgroup_id_y 0
		.amdhsa_system_sgpr_workgroup_id_z 0
		.amdhsa_system_sgpr_workgroup_info 0
		.amdhsa_system_vgpr_workitem_id 2
		.amdhsa_next_free_vgpr 256
		.amdhsa_next_free_sgpr 100
		.amdhsa_accum_offset 256
		.amdhsa_reserve_vcc 1
		.amdhsa_float_round_mode_32 0
		.amdhsa_float_round_mode_16_64 0
		.amdhsa_float_denorm_mode_32 3
		.amdhsa_float_denorm_mode_16_64 3
		.amdhsa_dx10_clamp 1
		.amdhsa_ieee_mode 1
		.amdhsa_fp16_overflow 0
		.amdhsa_tg_split 0
		.amdhsa_exception_fp_ieee_invalid_op 0
		.amdhsa_exception_fp_denorm_src 0
		.amdhsa_exception_fp_ieee_div_zero 0
		.amdhsa_exception_fp_ieee_overflow 0
		.amdhsa_exception_fp_ieee_underflow 0
		.amdhsa_exception_fp_ieee_inexact 0
		.amdhsa_exception_int_div_zero 0
	.end_amdhsa_kernel

amdhsa.kernels:
  - .agpr_count:     0
    .args:
      - .offset:         0
        .size:           240
        .value_kind:     by_value
      - .offset:         240
        .size:           4
        .value_kind:     hidden_block_count_x
      - .offset:         244
        .size:           4
        .value_kind:     hidden_block_count_y
      - .offset:         248
        .size:           4
        .value_kind:     hidden_block_count_z
      - .offset:         252
        .size:           2
        .value_kind:     hidden_group_size_x
      - .offset:         254
        .size:           2
        .value_kind:     hidden_group_size_y
      - .offset:         256
        .size:           2
        .value_kind:     hidden_group_size_z
      - .offset:         258
        .size:           2
        .value_kind:     hidden_remainder_x
      - .offset:         260
        .size:           2
        .value_kind:     hidden_remainder_y
      - .offset:         262
        .size:           2
        .value_kind:     hidden_remainder_z
      - .offset:         280
        .size:           8
        .value_kind:     hidden_global_offset_x
      - .offset:         288
        .size:           8
        .value_kind:     hidden_global_offset_y
      - .offset:         296
        .size:           8
        .value_kind:     hidden_global_offset_z
      - .offset:         304
        .size:           2
        .value_kind:     hidden_grid_dims
      - .offset:         328
        .size:           8
        .value_kind:     hidden_multigrid_sync_arg
      - .offset:         360
        .size:           4
        .value_kind:     hidden_dynamic_lds_size
    .group_segment_fixed_size: 0
    .kernarg_segment_align: 8
    .kernarg_segment_size: 496
    .language:       OpenCL C
    .language_version:
      - 2
      - 0
    .max_flat_workgroup_size: 512
    .name:           _Z9hymba_fwd4Args
    .private_segment_fixed_size: 0
    .sgpr_count:     106
    .sgpr_spill_count: 118
    .symbol:         _Z9hymba_fwd4Args.kd
    .uniform_work_group_size: 1
    .uses_dynamic_stack: false
    .vgpr_count:     256
    .vgpr_spill_count: 0
    .wavefront_size: 64
